# phase 0: four-row wave sum via DPP and permlane swaps instead of 24 ds_bpermute round trips (on top of the nt loads)
# speedup vs baseline: 1.0043x; 1.0008x over previous
.LBB0_81:
	v_add_co_u32_e32 v0, vcc, 0xffffd000, v70
	s_and_b32 s4, s0, 0xfffff000
	s_nop 0
	v_addc_co_u32_e32 v1, vcc, -1, v71, vcc
	global_load_dwordx4 v[60:63], v[0:1], off offset:-3072 nt
	s_waitcnt lgkmcnt(3)
	global_load_dwordx4 v[56:59], v[0:1], off offset:-2048 nt
	s_waitcnt lgkmcnt(2)
	global_load_dwordx4 v[48:51], v[0:1], off offset:-1024 nt
	s_waitcnt lgkmcnt(0)
	global_load_dwordx4 v[44:47], v[0:1], off nt
	v_add_co_u32_e32 v0, vcc, 0xffffe000, v70
	s_ashr_i32 s5, s4, 31
	s_nop 0
	v_addc_co_u32_e32 v1, vcc, -1, v71, vcc
	global_load_dwordx4 v[40:43], v[0:1], off offset:-3072 nt
	global_load_dwordx4 v[36:39], v[0:1], off offset:-2048 nt
	global_load_dwordx4 v[32:35], v[0:1], off offset:-1024 nt
	global_load_dwordx4 v[28:31], v[0:1], off nt
	v_add_co_u32_e32 v72, vcc, 0xfffff000, v70
	s_waitcnt vmcnt(7)
	v_mul_f32_e32 v64, v61, v61
	v_addc_co_u32_e32 v73, vcc, -1, v71, vcc
	global_load_dwordx4 v[20:23], v[72:73], off offset:-3072 nt
	global_load_dwordx4 v[24:27], v[72:73], off offset:-2048 nt
	global_load_dwordx4 v[16:19], v[72:73], off offset:-1024 nt
	global_load_dwordx4 v[12:15], v[70:71], off offset:-4096 nt
	global_load_dwordx4 v[8:11], v[70:71], off offset:-3072 nt
	global_load_dwordx4 v[4:7], v[70:71], off offset:-2048 nt
	global_load_dwordx4 v[0:3], v[70:71], off offset:-1024 nt
	global_load_dwordx4 v[52:55], v[70:71], off nt
	v_mul_f32_e32 v73, v63, v63
	v_cvt_pk_bf16_f32 v72, v60, v61
	s_waitcnt vmcnt(14)
	v_mul_f32_e32 v61, v57, v57
	v_mul_f32_e32 v84, v59, v59
	s_waitcnt vmcnt(13)
	v_mul_f32_e32 v85, v49, v49
	v_mul_f32_e32 v86, v51, v51
	s_waitcnt vmcnt(12)
	v_mul_f32_e32 v87, v45, v45
	v_mul_f32_e32 v88, v47, v47
	v_fmac_f32_e32 v64, v60, v60
	v_fmac_f32_e32 v73, v62, v62
	v_fmac_f32_e32 v61, v56, v56
	v_fmac_f32_e32 v84, v58, v58
	v_fmac_f32_e32 v85, v48, v48
	v_fmac_f32_e32 v86, v50, v50
	v_fmac_f32_e32 v87, v44, v44
	v_fmac_f32_e32 v88, v46, v46
	s_waitcnt vmcnt(11)
	v_mul_f32_e32 v60, v41, v41
	v_mul_f32_e32 v89, v43, v43
	s_waitcnt vmcnt(10)
	v_mul_f32_e32 v90, v37, v37
	v_mul_f32_e32 v91, v39, v39
	v_add_f32_e32 v64, v64, v73
	v_add_f32_e32 v61, v61, v84
	v_add_f32_e32 v73, v85, v86
	v_add_f32_e32 v84, v87, v88
	v_fmac_f32_e32 v60, v40, v40
	v_fmac_f32_e32 v89, v42, v42
	v_fmac_f32_e32 v90, v36, v36
	v_fmac_f32_e32 v91, v38, v38
	v_add_f32_e32 v61, v64, v61
	v_add_f32_e32 v60, v60, v89
	v_add_f32_e32 v64, v90, v91
	v_add_f32_e32 v61, v61, v73
	v_add_f32_e32 v60, v60, v64
	v_add_f32_e32 v61, v61, v84
	s_waitcnt vmcnt(9)
	v_mul_f32_e32 v92, v33, v33
	v_mul_f32_e32 v93, v35, v35
	s_waitcnt vmcnt(8)
	v_mul_f32_e32 v94, v29, v29
	v_mul_f32_e32 v95, v31, v31
	v_fmac_f32_e32 v92, v32, v32
	v_fmac_f32_e32 v93, v34, v34
	v_fmac_f32_e32 v94, v28, v28
	v_fmac_f32_e32 v95, v30, v30
	v_add_f32_e32 v89, v92, v93
	v_add_f32_e32 v90, v94, v95
	v_add_f32_e32 v60, v60, v89
	v_add_f32_e32 v60, v60, v90
	s_waitcnt vmcnt(7)
	v_mul_f32_e32 v85, v21, v21
	v_mul_f32_e32 v86, v23, v23
	s_waitcnt vmcnt(6)
	v_mul_f32_e32 v87, v25, v25
	v_mul_f32_e32 v88, v27, v27
	v_fmac_f32_e32 v85, v20, v20
	v_fmac_f32_e32 v86, v22, v22
	v_fmac_f32_e32 v87, v24, v24
	v_fmac_f32_e32 v88, v26, v26
	v_add_f32_e32 v64, v85, v86
	v_add_f32_e32 v73, v87, v88
	v_add_f32_e32 v64, v64, v73
	s_waitcnt vmcnt(5)
	v_mul_f32_e32 v73, v17, v17
	v_mul_f32_e32 v84, v19, v19
	v_fmac_f32_e32 v73, v16, v16
	v_fmac_f32_e32 v84, v18, v18
	v_add_f32_e32 v73, v73, v84
	v_add_f32_e32 v64, v64, v73
	s_waitcnt vmcnt(4)
	v_mul_f32_e32 v73, v13, v13
	v_mul_f32_e32 v84, v15, v15
	v_fmac_f32_e32 v73, v12, v12
	v_fmac_f32_e32 v84, v14, v14
	v_add_f32_e32 v73, v73, v84
	v_add_f32_e32 v64, v64, v73
	s_waitcnt vmcnt(3)
	v_mul_f32_e32 v73, v9, v9
	v_mul_f32_e32 v84, v11, v11
	v_fmac_f32_e32 v73, v8, v8
	v_fmac_f32_e32 v84, v10, v10
	v_add_f32_e32 v73, v73, v84
	s_waitcnt vmcnt(2)
	v_mul_f32_e32 v84, v5, v5
	v_mul_f32_e32 v85, v7, v7
	v_fmac_f32_e32 v84, v4, v4
	v_fmac_f32_e32 v85, v6, v6
	v_add_f32_e32 v84, v84, v85
	v_add_f32_e32 v73, v73, v84
	s_waitcnt vmcnt(1)
	v_mul_f32_e32 v84, v1, v1
	v_mul_f32_e32 v85, v3, v3
	v_fmac_f32_e32 v84, v0, v0
	v_fmac_f32_e32 v85, v2, v2
	v_add_f32_e32 v84, v84, v85
	v_add_f32_e32 v73, v73, v84
	s_waitcnt vmcnt(0)
	v_mul_f32_e32 v84, v53, v53
	v_mul_f32_e32 v85, v55, v55
	v_fmac_f32_e32 v84, v52, v52
	v_fmac_f32_e32 v85, v54, v54
	v_add_f32_e32 v84, v84, v85
	v_add_f32_e32 v84, v73, v84
	v_cvt_pk_bf16_f32 v73, v62, v63
	v_add_f32_dpp v61, v61, v61 quad_perm:[1,0,3,2] row_mask:0xf bank_mask:0xf
	v_add_f32_dpp v62, v60, v60 quad_perm:[1,0,3,2] row_mask:0xf bank_mask:0xf
	v_add_f32_dpp v63, v64, v64 quad_perm:[1,0,3,2] row_mask:0xf bank_mask:0xf
	v_add_f32_dpp v64, v84, v84 quad_perm:[1,0,3,2] row_mask:0xf bank_mask:0xf
	v_cvt_pk_bf16_f32 v60, v56, v57
	v_add_f32_dpp v56, v61, v61 quad_perm:[2,3,0,1] row_mask:0xf bank_mask:0xf
	v_add_f32_dpp v57, v62, v62 quad_perm:[2,3,0,1] row_mask:0xf bank_mask:0xf
	v_add_f32_dpp v62, v63, v63 quad_perm:[2,3,0,1] row_mask:0xf bank_mask:0xf
	v_add_f32_dpp v63, v64, v64 quad_perm:[2,3,0,1] row_mask:0xf bank_mask:0xf
	v_cvt_pk_bf16_f32 v61, v58, v59
	v_add_f32_dpp v56, v56, v56 row_half_mirror row_mask:0xf bank_mask:0xf
	v_add_f32_dpp v57, v57, v57 row_half_mirror row_mask:0xf bank_mask:0xf
	v_add_f32_dpp v59, v62, v62 row_half_mirror row_mask:0xf bank_mask:0xf
	v_add_f32_dpp v62, v63, v63 row_half_mirror row_mask:0xf bank_mask:0xf
	v_cvt_pk_bf16_f32 v58, v48, v49
	v_add_f32_dpp v48, v56, v56 row_mirror row_mask:0xf bank_mask:0xf
	v_add_f32_dpp v49, v57, v57 row_mirror row_mask:0xf bank_mask:0xf
	v_add_f32_dpp v57, v59, v59 row_mirror row_mask:0xf bank_mask:0xf
	v_add_f32_dpp v62, v62, v62 row_mirror row_mask:0xf bank_mask:0xf
	v_mov_b32_e32 v56, v48
	v_mov_b32_e32 v63, v49
	v_mov_b32_e32 v64, v57
	v_mov_b32_e32 v84, v62
	v_cvt_pk_bf16_f32 v59, v50, v51
	v_permlane16_swap_b32_e32 v48, v56
	v_add_f32_e32 v56, v48, v56
	v_permlane16_swap_b32_e32 v49, v63
	v_add_f32_e32 v50, v49, v63
	v_permlane16_swap_b32_e32 v57, v64
	v_add_f32_e32 v49, v57, v64
	v_permlane16_swap_b32_e32 v62, v84
	v_add_f32_e32 v48, v62, v84
	v_cvt_pk_bf16_f32 v63, v46, v47
	v_mov_b32_e32 v57, v56
	v_mov_b32_e32 v51, v50
	v_mov_b32_e32 v47, v49
	v_mov_b32_e32 v46, v48
	v_add_co_u32_e32 v84, vcc, s1, v68
	v_cvt_pk_bf16_f32 v62, v44, v45
	s_nop 0
	v_addc_co_u32_e32 v85, vcc, -1, v69, vcc
	v_lshl_add_u64 v[44:45], s[4:5], 2, v[66:67]
	v_permlane32_swap_b32_e32 v56, v57
	v_permlane32_swap_b32_e32 v50, v51
	v_permlane32_swap_b32_e32 v49, v47
	v_permlane32_swap_b32_e32 v48, v46
	global_store_dwordx2 v[84:85], v[72:73], off offset:-3584
	global_store_dwordx2 v[84:85], v[60:61], off offset:-3072
	global_store_dwordx2 v[84:85], v[58:59], off offset:-2560
	global_store_dwordx2 v[84:85], v[62:63], off offset:-2048
	s_and_saveexec_b64 s[12:13], s[2:3]
	s_cbranch_execz .LBB0_83
	s_waitcnt lgkmcnt(3)
	v_add_f32_e32 v56, v56, v57
	v_fmamk_f32 v56, v56, 0x3a800000, v82
	v_mul_f32_e32 v57, 0x4f800000, v56
	v_cmp_gt_f32_e32 vcc, s7, v56
	s_nop 1
	v_cndmask_b32_e32 v56, v56, v57, vcc
	v_sqrt_f32_e32 v57, v56
	s_nop 0
	v_add_u32_e32 v58, -1, v57
	v_fma_f32 v60, -v58, v57, v56
	v_add_u32_e32 v59, 1, v57
	v_cmp_ge_f32_e64 s[4:5], 0, v60
	s_nop 1
	v_cndmask_b32_e64 v58, v57, v58, s[4:5]
	v_fma_f32 v57, -v59, v57, v56
	v_cmp_lt_f32_e64 s[4:5], 0, v57
	s_nop 1
	v_cndmask_b32_e64 v57, v58, v59, s[4:5]
	v_mul_f32_e32 v58, 0x37800000, v57
	v_cndmask_b32_e32 v57, v57, v58, vcc
	v_cmp_class_f32_e32 vcc, v56, v83
	s_nop 1
	v_cndmask_b32_e32 v56, v57, v56, vcc
	v_div_scale_f32 v57, s[4:5], v56, v56, 1.0
	v_rcp_f32_e32 v58, v57
	s_and_b32 s4, s0, 0xffc
	v_fma_f32 v59, -v57, v58, 1.0
	v_fmac_f32_e32 v58, v59, v58
	v_div_scale_f32 v59, vcc, 1.0, v56, 1.0
	v_mul_f32_e32 v60, v59, v58
	v_fma_f32 v61, -v57, v60, v59
	v_fmac_f32_e32 v60, v61, v58
	v_fma_f32 v57, -v57, v60, v59
	v_div_fmas_f32 v57, v57, v58, v60
	v_div_fixup_f32 v58, v57, v56, 1.0
	v_lshlrev_b32_e64 v56, v75, s0
	v_and_b32_e32 v56, 0xff0, v56
	v_lshrrev_b32_e64 v59, v74, s4
	v_lshlrev_b32_e32 v64, 2, v56
	v_lshl_add_u64 v[56:57], v[44:45], 0, v[64:65]
	v_lshlrev_b32_e32 v64, 2, v59
	v_lshl_add_u64 v[56:57], v[56:57], 0, v[64:65]
	global_store_dword v[56:57], v58, off
